# first phase also stores its bf16 xb rows and transposed weights non-temporal
# baseline (speedup 1.0000x reference)
.LBB0_20:
	s_movk_i32 s3, 0x2bff
	v_cmp_lt_i32_e32 vcc, s3, v16
	s_and_saveexec_b64 s[30:31], vcc
	s_xor_b64 s[30:31], exec, s[30:31]
	s_cbranch_execz .LBB0_37
	s_movk_i32 s3, 0x41ff
	v_cmp_lt_u32_e32 vcc, s3, v16
	s_and_saveexec_b64 s[60:61], vcc
	s_xor_b64 s[60:61], exec, s[60:61]
	s_cbranch_execz .LBB0_34
	s_movk_i32 s3, 0x49ff
	v_cmp_lt_u32_e32 vcc, s3, v16
	s_and_saveexec_b64 s[62:63], vcc
	s_xor_b64 s[62:63], exec, s[62:63]
	s_cbranch_execz .LBB0_28
	s_movk_i32 s3, 0x4dff
	v_and_b32_e32 v2, 0x3e0, v14
	v_cmp_lt_u32_e32 vcc, s3, v16
	v_lshlrev_b32_e32 v6, 2, v2
	v_or_b32_e32 v11, v2, v101
	v_or_b32_e32 v10, v2, v103
	v_or_b32_e32 v9, v2, v104
	v_or_b32_e32 v8, v2, v105
	s_and_saveexec_b64 s[64:65], vcc
	s_xor_b64 s[64:65], exec, s[64:65]
	s_cbranch_execz .LBB0_25
	v_and_b32_e32 v2, 0x7fffffc0, v15
	v_add_u32_e32 v4, 0xffff6400, v2
	v_or_b32_e32 v2, v4, v73
	v_lshlrev_b64 v[12:13], 12, v[2:3]
	s_waitcnt lgkmcnt(0)
	v_lshl_add_u64 v[12:13], s[26:27], 0, v[12:13]
	v_mov_b32_e32 v7, v3
	v_lshl_add_u64 v[6:7], v[12:13], 0, v[6:7]
	v_lshlrev_b32_e32 v2, 2, v70
	v_lshl_add_u64 v[6:7], v[6:7], 0, v[2:3]
	v_add_co_u32_e32 v12, vcc, 0x2000, v6
	v_mov_b32_e32 v5, v3
	s_nop 0
	v_addc_co_u32_e32 v13, vcc, 0, v7, vcc
	v_add_co_u32_e32 v18, vcc, 0x4000, v6
	s_nop 1
	v_addc_co_u32_e32 v19, vcc, 0, v7, vcc
	v_add_co_u32_e32 v20, vcc, 0x6000, v6
	s_nop 1
	v_addc_co_u32_e32 v21, vcc, 0, v7, vcc
	v_add_co_u32_e32 v22, vcc, 0x8000, v6
	s_nop 1
	v_addc_co_u32_e32 v23, vcc, 0, v7, vcc
	v_add_co_u32_e32 v24, vcc, 0xa000, v6
	s_nop 1
	v_addc_co_u32_e32 v25, vcc, 0, v7, vcc
	v_add_co_u32_e32 v26, vcc, 0xc000, v6
	s_nop 1
	v_addc_co_u32_e32 v27, vcc, 0, v7, vcc
	v_add_co_u32_e32 v28, vcc, 0xe000, v6
	s_nop 1
	v_addc_co_u32_e32 v29, vcc, 0, v7, vcc
	global_load_dword v2, v[6:7], off nt
	global_load_dword v17, v[12:13], off nt
	global_load_dword v32, v[18:19], off nt
	global_load_dword v33, v[20:21], off nt
	global_load_dword v34, v[22:23], off nt
	global_load_dword v35, v[24:25], off nt
	global_load_dword v36, v[26:27], off nt
	global_load_dword v37, v[28:29], off nt
	v_add_co_u32_e32 v12, vcc, 0x10000, v6
	s_nop 1
	v_addc_co_u32_e32 v13, vcc, 0, v7, vcc
	v_add_co_u32_e32 v18, vcc, 0x12000, v6
	s_nop 1
	v_addc_co_u32_e32 v19, vcc, 0, v7, vcc
	v_add_co_u32_e32 v20, vcc, 0x14000, v6
	s_nop 1
	v_addc_co_u32_e32 v21, vcc, 0, v7, vcc
	v_add_co_u32_e32 v22, vcc, 0x16000, v6
	s_nop 1
	v_addc_co_u32_e32 v23, vcc, 0, v7, vcc
	v_add_co_u32_e32 v24, vcc, 0x18000, v6
	s_nop 1
	v_addc_co_u32_e32 v25, vcc, 0, v7, vcc
	v_add_co_u32_e32 v26, vcc, 0x1a000, v6
	s_nop 1
	v_addc_co_u32_e32 v27, vcc, 0, v7, vcc
	v_add_co_u32_e32 v28, vcc, 0x1c000, v6
	s_nop 1
	v_addc_co_u32_e32 v29, vcc, 0, v7, vcc
	v_add_co_u32_e32 v30, vcc, 0x1e000, v6
	s_nop 1
	v_addc_co_u32_e32 v31, vcc, 0, v7, vcc
	global_load_dword v38, v[12:13], off nt
	global_load_dword v39, v[18:19], off nt
	global_load_dword v40, v[20:21], off nt
	global_load_dword v41, v[22:23], off nt
	global_load_dword v42, v[24:25], off nt
	global_load_dword v43, v[26:27], off nt
	global_load_dword v44, v[28:29], off nt
	global_load_dword v45, v[30:31], off nt
	v_add_co_u32_e32 v12, vcc, s75, v6
	s_nop 1
	v_addc_co_u32_e32 v13, vcc, 0, v7, vcc
	v_add_co_u32_e32 v18, vcc, 0x22000, v6
	s_nop 1
	v_addc_co_u32_e32 v19, vcc, 0, v7, vcc
	v_add_co_u32_e32 v20, vcc, 0x24000, v6
	s_nop 1
	v_addc_co_u32_e32 v21, vcc, 0, v7, vcc
	v_add_co_u32_e32 v22, vcc, 0x26000, v6
	s_nop 1
	v_addc_co_u32_e32 v23, vcc, 0, v7, vcc
	v_add_co_u32_e32 v24, vcc, 0x28000, v6
	s_nop 1
	v_addc_co_u32_e32 v25, vcc, 0, v7, vcc
	v_add_co_u32_e32 v26, vcc, 0x2a000, v6
	s_nop 1
	v_addc_co_u32_e32 v27, vcc, 0, v7, vcc
	v_add_co_u32_e32 v28, vcc, 0x2c000, v6
	s_nop 1
	v_addc_co_u32_e32 v29, vcc, 0, v7, vcc
	v_add_co_u32_e32 v30, vcc, 0x2e000, v6
	s_nop 1
	v_addc_co_u32_e32 v31, vcc, 0, v7, vcc
	global_load_dword v46, v[12:13], off nt
	global_load_dword v47, v[18:19], off nt
	global_load_dword v48, v[20:21], off nt
	global_load_dword v49, v[22:23], off nt
	global_load_dword v50, v[24:25], off nt
	global_load_dword v51, v[26:27], off nt
	global_load_dword v52, v[28:29], off nt
	s_nop 0
	global_load_dword v30, v[30:31], off nt
	v_add_co_u32_e32 v12, vcc, 0x30000, v6
	s_nop 1
	v_addc_co_u32_e32 v13, vcc, 0, v7, vcc
	v_add_co_u32_e32 v18, vcc, 0x32000, v6
	s_nop 1
	v_addc_co_u32_e32 v19, vcc, 0, v7, vcc
	v_add_co_u32_e32 v20, vcc, 0x34000, v6
	s_nop 1
	v_addc_co_u32_e32 v21, vcc, 0, v7, vcc
	v_add_co_u32_e32 v22, vcc, 0x36000, v6
	s_nop 1
	v_addc_co_u32_e32 v23, vcc, 0, v7, vcc
	v_add_co_u32_e32 v24, vcc, 0x38000, v6
	s_nop 1
	v_addc_co_u32_e32 v25, vcc, 0, v7, vcc
	v_add_co_u32_e32 v26, vcc, 0x3a000, v6
	s_nop 1
	v_addc_co_u32_e32 v27, vcc, 0, v7, vcc
	v_add_co_u32_e32 v28, vcc, 0x3c000, v6
	s_nop 1
	v_addc_co_u32_e32 v29, vcc, 0, v7, vcc
	v_add_co_u32_e32 v6, vcc, s79, v6
	s_nop 1
	v_addc_co_u32_e32 v7, vcc, 0, v7, vcc
	global_load_dword v12, v[12:13], off nt
	s_nop 0
	global_load_dword v13, v[18:19], off nt
	global_load_dword v31, v[20:21], off nt
	global_load_dword v53, v[22:23], off nt
	global_load_dword v54, v[24:25], off nt
	s_nop 0
	global_load_dword v26, v[26:27], off nt
	s_nop 0
	global_load_dword v27, v[28:29], off nt
	s_nop 0
	global_load_dword v28, v[6:7], off nt
	v_lshl_add_u64 v[6:7], v[4:5], 2, v[76:77]
	global_load_dwordx4 v[18:21], v[6:7], off
	global_load_dwordx4 v[22:25], v[6:7], off offset:16
	s_waitcnt vmcnt(32)
	ds_write2_b32 v100, v2, v17 offset1:66
	s_waitcnt vmcnt(30)
	ds_write2_b32 v100, v32, v33 offset0:132 offset1:198
	v_add_u32_e32 v2, 0x400, v100
	s_waitcnt vmcnt(28)
	ds_write2_b32 v2, v34, v35 offset0:8 offset1:74
	s_waitcnt vmcnt(26)
	ds_write2_b32 v2, v36, v37 offset0:140 offset1:206
	v_add_u32_e32 v2, 0x800, v100
	s_waitcnt vmcnt(24)
	ds_write2_b32 v2, v38, v39 offset0:16 offset1:82
	s_waitcnt vmcnt(22)
	ds_write2_b32 v2, v40, v41 offset0:148 offset1:214
	v_add_u32_e32 v2, 0xc00, v100
	s_waitcnt vmcnt(20)
	ds_write2_b32 v2, v42, v43 offset0:24 offset1:90
	s_waitcnt vmcnt(18)
	ds_write2_b32 v2, v44, v45 offset0:156 offset1:222
	v_add_u32_e32 v2, 0x1000, v100
	s_waitcnt vmcnt(16)
	ds_write2_b32 v2, v46, v47 offset0:32 offset1:98
	s_waitcnt vmcnt(14)
	ds_write2_b32 v2, v48, v49 offset0:164 offset1:230
	v_add_u32_e32 v2, 0x1400, v100
	s_waitcnt vmcnt(12)
	ds_write2_b32 v2, v50, v51 offset0:40 offset1:106
	s_waitcnt vmcnt(10)
	ds_write2_b32 v2, v52, v30 offset0:172 offset1:238
	v_add_u32_e32 v2, 0x1800, v100
	s_waitcnt vmcnt(8)
	ds_write2_b32 v2, v12, v13 offset0:48 offset1:114
	s_waitcnt vmcnt(6)
	ds_write2_b32 v2, v31, v53 offset0:180 offset1:246
	v_add_u32_e32 v2, 0x1c00, v100
	s_waitcnt vmcnt(4)
	ds_write2_b32 v2, v54, v26 offset0:56 offset1:122
	s_waitcnt vmcnt(2)
	ds_write2_b32 v2, v27, v28 offset0:188 offset1:254
	s_waitcnt lgkmcnt(0)
	ds_read2_b32 v[6:7], v102 offset1:33
	v_lshl_add_u64 v[12:13], v[4:5], 1, v[78:79]
	s_waitcnt vmcnt(1) lgkmcnt(0)
	v_mul_f32_e32 v2, v18, v6
	v_mul_f32_e32 v6, v19, v7
	v_cvt_pk_bf16_f32 v26, v2, v6
	ds_read2_b32 v[6:7], v102 offset0:66 offset1:99
	s_waitcnt lgkmcnt(0)
	v_mul_f32_e32 v2, v20, v6
	v_mul_f32_e32 v6, v21, v7
	v_cvt_pk_bf16_f32 v27, v2, v6
	ds_read2_b32 v[6:7], v102 offset0:132 offset1:165
	s_waitcnt vmcnt(0) lgkmcnt(0)
	v_mul_f32_e32 v2, v22, v6
	v_mul_f32_e32 v6, v23, v7
	v_cvt_pk_bf16_f32 v28, v2, v6
	ds_read2_b32 v[6:7], v102 offset0:198 offset1:231
	s_waitcnt lgkmcnt(0)
	v_mul_f32_e32 v2, v24, v6
	v_mul_f32_e32 v6, v25, v7
	v_cvt_pk_bf16_f32 v29, v2, v6
	ds_read2_b32 v[6:7], v102 offset0:8 offset1:41
	v_lshlrev_b32_e32 v2, 11, v11
	v_lshl_add_u64 v[4:5], v[12:13], 0, v[2:3]
	global_store_dwordx4 v[4:5], v[26:29], off nt
	s_waitcnt lgkmcnt(0)
	v_mul_f32_e32 v4, v19, v7
	v_mul_f32_e32 v2, v18, v6
	v_cvt_pk_bf16_f32 v4, v2, v4
	ds_read2_b32 v[6:7], v102 offset0:74 offset1:107
	s_waitcnt lgkmcnt(0)
	v_mul_f32_e32 v5, v21, v7
	v_mul_f32_e32 v2, v20, v6
	v_cvt_pk_bf16_f32 v5, v2, v5
	ds_read2_b32 v[6:7], v102 offset0:140 offset1:173
	s_waitcnt lgkmcnt(0)
	v_mul_f32_e32 v2, v22, v6
	v_mul_f32_e32 v6, v23, v7
	v_cvt_pk_bf16_f32 v6, v2, v6
	ds_read2_b32 v[26:27], v102 offset0:206 offset1:239
	s_waitcnt lgkmcnt(0)
	v_mul_f32_e32 v7, v25, v27
	v_mul_f32_e32 v2, v24, v26
	v_cvt_pk_bf16_f32 v7, v2, v7
	ds_read2_b32 v[26:27], v102 offset0:16 offset1:49
	v_lshlrev_b32_e32 v2, 11, v10
	v_lshl_add_u64 v[10:11], v[12:13], 0, v[2:3]
	global_store_dwordx4 v[10:11], v[4:7], off nt
	s_waitcnt lgkmcnt(0)
	v_mul_f32_e32 v2, v18, v26
	v_mul_f32_e32 v4, v19, v27
	v_cvt_pk_bf16_f32 v4, v2, v4
	ds_read2_b32 v[6:7], v102 offset0:82 offset1:115
	s_waitcnt lgkmcnt(0)
	v_mul_f32_e32 v5, v21, v7
	v_mul_f32_e32 v2, v20, v6
	v_cvt_pk_bf16_f32 v5, v2, v5
	ds_read2_b32 v[6:7], v102 offset0:148 offset1:181
	s_waitcnt lgkmcnt(0)
	v_mul_f32_e32 v2, v22, v6
	v_mul_f32_e32 v6, v23, v7
	v_cvt_pk_bf16_f32 v6, v2, v6
	ds_read2_b32 v[10:11], v102 offset0:214 offset1:247
	s_waitcnt lgkmcnt(0)
	v_mul_f32_e32 v7, v25, v11
	v_mul_f32_e32 v2, v24, v10
	v_cvt_pk_bf16_f32 v7, v2, v7
	ds_read2_b32 v[10:11], v102 offset0:24 offset1:57
	v_lshlrev_b32_e32 v2, 11, v9
	v_lshl_add_u64 v[26:27], v[12:13], 0, v[2:3]
	global_store_dwordx4 v[26:27], v[4:7], off nt
	s_waitcnt lgkmcnt(0)
	v_mul_f32_e32 v2, v18, v10
	v_mul_f32_e32 v4, v19, v11
	v_cvt_pk_bf16_f32 v4, v2, v4
	ds_read2_b32 v[6:7], v102 offset0:90 offset1:123
	s_waitcnt lgkmcnt(0)
	v_mul_f32_e32 v5, v21, v7
	v_mul_f32_e32 v2, v20, v6
	v_cvt_pk_bf16_f32 v5, v2, v5
	ds_read2_b32 v[6:7], v102 offset0:156 offset1:189
	s_waitcnt lgkmcnt(0)
	v_mul_f32_e32 v2, v22, v6
	v_mul_f32_e32 v6, v23, v7
	v_cvt_pk_bf16_f32 v6, v2, v6
	ds_read2_b32 v[10:11], v102 offset0:222 offset1:255
	s_waitcnt lgkmcnt(0)
	v_mul_f32_e32 v2, v24, v10
	v_mul_f32_e32 v7, v25, v11
	v_cvt_pk_bf16_f32 v7, v2, v7
	v_lshlrev_b32_e32 v2, 11, v8
	v_lshl_add_u64 v[8:9], v[12:13], 0, v[2:3]
	global_store_dwordx4 v[8:9], v[4:7], off nt
	s_waitcnt lgkmcnt(0)
.LBB0_25:
	s_andn2_saveexec_b64 s[64:65], s[64:65]
	s_cbranch_execz .LBB0_27
	v_and_b32_e32 v2, 0xffc0, v15
	v_add_u32_e32 v4, 0xffff6c00, v2
	v_or_b32_e32 v2, v4, v73
	v_lshlrev_b64 v[12:13], 12, v[2:3]
	s_waitcnt lgkmcnt(0)
	v_lshl_add_u64 v[12:13], s[24:25], 0, v[12:13]
	v_mov_b32_e32 v7, v3
	v_lshl_add_u64 v[6:7], v[12:13], 0, v[6:7]
	v_lshlrev_b32_e32 v2, 2, v70
	v_lshl_add_u64 v[6:7], v[6:7], 0, v[2:3]
	v_add_co_u32_e32 v12, vcc, 0x2000, v6
	s_nop 1
	v_addc_co_u32_e32 v13, vcc, 0, v7, vcc
	v_add_co_u32_e32 v18, vcc, 0x4000, v6
	s_nop 1
	v_addc_co_u32_e32 v19, vcc, 0, v7, vcc
	v_add_co_u32_e32 v20, vcc, 0x6000, v6
	s_nop 1
	v_addc_co_u32_e32 v21, vcc, 0, v7, vcc
	v_add_co_u32_e32 v22, vcc, 0x8000, v6
	s_nop 1
	v_addc_co_u32_e32 v23, vcc, 0, v7, vcc
	v_add_co_u32_e32 v24, vcc, 0xa000, v6
	s_nop 1
	v_addc_co_u32_e32 v25, vcc, 0, v7, vcc
	v_add_co_u32_e32 v26, vcc, 0xc000, v6
	s_nop 1
	v_addc_co_u32_e32 v27, vcc, 0, v7, vcc
	v_add_co_u32_e32 v28, vcc, 0xe000, v6
	s_nop 1
	v_addc_co_u32_e32 v29, vcc, 0, v7, vcc
	global_load_dword v2, v[6:7], off nt
	global_load_dword v5, v[12:13], off nt
	global_load_dword v17, v[18:19], off nt
	global_load_dword v32, v[20:21], off nt
	global_load_dword v33, v[22:23], off nt
	global_load_dword v34, v[24:25], off nt
	global_load_dword v35, v[26:27], off nt
	global_load_dword v36, v[28:29], off nt
	v_add_co_u32_e32 v12, vcc, 0x10000, v6
	s_nop 1
	v_addc_co_u32_e32 v13, vcc, 0, v7, vcc
	v_add_co_u32_e32 v18, vcc, 0x12000, v6
	s_nop 1
	v_addc_co_u32_e32 v19, vcc, 0, v7, vcc
	v_add_co_u32_e32 v20, vcc, 0x14000, v6
	s_nop 1
	v_addc_co_u32_e32 v21, vcc, 0, v7, vcc
	v_add_co_u32_e32 v22, vcc, 0x16000, v6
	s_nop 1
	v_addc_co_u32_e32 v23, vcc, 0, v7, vcc
	v_add_co_u32_e32 v24, vcc, 0x18000, v6
	s_nop 1
	v_addc_co_u32_e32 v25, vcc, 0, v7, vcc
	v_add_co_u32_e32 v26, vcc, 0x1a000, v6
	s_nop 1
	v_addc_co_u32_e32 v27, vcc, 0, v7, vcc
	v_add_co_u32_e32 v28, vcc, 0x1c000, v6
	s_nop 1
	v_addc_co_u32_e32 v29, vcc, 0, v7, vcc
	v_add_co_u32_e32 v30, vcc, 0x1e000, v6
	s_nop 1
	v_addc_co_u32_e32 v31, vcc, 0, v7, vcc
	global_load_dword v37, v[12:13], off nt
	global_load_dword v38, v[18:19], off nt
	global_load_dword v39, v[20:21], off nt
	global_load_dword v40, v[22:23], off nt
	global_load_dword v41, v[24:25], off nt
	global_load_dword v42, v[26:27], off nt
	global_load_dword v43, v[28:29], off nt
	global_load_dword v44, v[30:31], off nt
	v_add_co_u32_e32 v12, vcc, s75, v6
	s_nop 1
	v_addc_co_u32_e32 v13, vcc, 0, v7, vcc
	v_add_co_u32_e32 v18, vcc, 0x22000, v6
	s_nop 1
	v_addc_co_u32_e32 v19, vcc, 0, v7, vcc
	v_add_co_u32_e32 v20, vcc, 0x24000, v6
	s_nop 1
	v_addc_co_u32_e32 v21, vcc, 0, v7, vcc
	v_add_co_u32_e32 v22, vcc, 0x26000, v6
	s_nop 1
	v_addc_co_u32_e32 v23, vcc, 0, v7, vcc
	v_add_co_u32_e32 v24, vcc, 0x28000, v6
	s_nop 1
	v_addc_co_u32_e32 v25, vcc, 0, v7, vcc
	v_add_co_u32_e32 v26, vcc, 0x2a000, v6
	s_nop 1
	v_addc_co_u32_e32 v27, vcc, 0, v7, vcc
	v_add_co_u32_e32 v28, vcc, 0x2c000, v6
	s_nop 1
	v_addc_co_u32_e32 v29, vcc, 0, v7, vcc
	v_add_co_u32_e32 v30, vcc, 0x2e000, v6
	s_nop 1
	v_addc_co_u32_e32 v31, vcc, 0, v7, vcc
	global_load_dword v45, v[12:13], off nt
	global_load_dword v46, v[18:19], off nt
	global_load_dword v47, v[20:21], off nt
	global_load_dword v48, v[22:23], off nt
	global_load_dword v49, v[24:25], off nt
	global_load_dword v50, v[26:27], off nt
	global_load_dword v51, v[28:29], off nt
	s_nop 0
	global_load_dword v30, v[30:31], off nt
	v_add_co_u32_e32 v12, vcc, 0x30000, v6
	s_nop 1
	v_addc_co_u32_e32 v13, vcc, 0, v7, vcc
	v_add_co_u32_e32 v18, vcc, 0x32000, v6
	s_nop 1
	v_addc_co_u32_e32 v19, vcc, 0, v7, vcc
	v_add_co_u32_e32 v20, vcc, 0x34000, v6
	s_nop 1
	v_addc_co_u32_e32 v21, vcc, 0, v7, vcc
	v_add_co_u32_e32 v22, vcc, 0x36000, v6
	s_nop 1
	v_addc_co_u32_e32 v23, vcc, 0, v7, vcc
	v_add_co_u32_e32 v24, vcc, 0x38000, v6
	s_nop 1
	v_addc_co_u32_e32 v25, vcc, 0, v7, vcc
	v_add_co_u32_e32 v26, vcc, 0x3a000, v6
	s_nop 1
	v_addc_co_u32_e32 v27, vcc, 0, v7, vcc
	v_add_co_u32_e32 v28, vcc, 0x3c000, v6
	s_nop 1
	v_addc_co_u32_e32 v29, vcc, 0, v7, vcc
	v_add_co_u32_e32 v6, vcc, s79, v6
	s_nop 1
	v_addc_co_u32_e32 v7, vcc, 0, v7, vcc
	global_load_dword v12, v[12:13], off nt
	s_nop 0
	global_load_dword v13, v[18:19], off nt
	s_nop 0
	global_load_dword v18, v[20:21], off nt
	global_load_dword v19, v[22:23], off nt
	s_nop 0
	global_load_dword v20, v[24:25], off nt
	global_load_dword v21, v[26:27], off nt
	global_load_dword v22, v[28:29], off nt
	s_nop 0
	global_load_dword v6, v[6:7], off nt
	s_waitcnt vmcnt(30)
	ds_write2_b32 v100, v2, v5 offset1:66
	s_waitcnt vmcnt(28)
	ds_write2_b32 v100, v17, v32 offset0:132 offset1:198
	v_add_u32_e32 v2, 0x400, v100
	s_waitcnt vmcnt(26)
	ds_write2_b32 v2, v33, v34 offset0:8 offset1:74
	s_waitcnt vmcnt(24)
	ds_write2_b32 v2, v35, v36 offset0:140 offset1:206
	v_add_u32_e32 v2, 0x800, v100
	s_waitcnt vmcnt(22)
	ds_write2_b32 v2, v37, v38 offset0:16 offset1:82
	s_waitcnt vmcnt(20)
	ds_write2_b32 v2, v39, v40 offset0:148 offset1:214
	v_add_u32_e32 v2, 0xc00, v100
	s_waitcnt vmcnt(18)
	ds_write2_b32 v2, v41, v42 offset0:24 offset1:90
	s_waitcnt vmcnt(16)
	ds_write2_b32 v2, v43, v44 offset0:156 offset1:222
	v_add_u32_e32 v2, 0x1000, v100
	s_waitcnt vmcnt(14)
	ds_write2_b32 v2, v45, v46 offset0:32 offset1:98
	s_waitcnt vmcnt(12)
	ds_write2_b32 v2, v47, v48 offset0:164 offset1:230
	v_add_u32_e32 v2, 0x1400, v100
	s_waitcnt vmcnt(10)
	ds_write2_b32 v2, v49, v50 offset0:40 offset1:106
	s_waitcnt vmcnt(8)
	ds_write2_b32 v2, v51, v30 offset0:172 offset1:238
	v_add_u32_e32 v2, 0x1800, v100
	s_waitcnt vmcnt(6)
	ds_write2_b32 v2, v12, v13 offset0:48 offset1:114
	s_waitcnt vmcnt(4)
	ds_write2_b32 v2, v18, v19 offset0:180 offset1:246
	v_add_u32_e32 v2, 0x1c00, v100
	s_waitcnt vmcnt(2)
	ds_write2_b32 v2, v20, v21 offset0:56 offset1:122
	s_waitcnt vmcnt(0)
	ds_write2_b32 v2, v22, v6 offset0:188 offset1:254
	s_waitcnt lgkmcnt(0)
	ds_read2_b32 v[6:7], v102 offset1:33
	s_waitcnt lgkmcnt(0)
	v_cvt_pk_bf16_f32 v18, v6, v7
	ds_read2_b32 v[6:7], v102 offset0:66 offset1:99
	s_waitcnt lgkmcnt(0)
	v_cvt_pk_bf16_f32 v19, v6, v7
	ds_read2_b32 v[6:7], v102 offset0:132 offset1:165
	v_mov_b32_e32 v5, v3
	s_waitcnt lgkmcnt(0)
	v_cvt_pk_bf16_f32 v20, v6, v7
	ds_read2_b32 v[6:7], v102 offset0:198 offset1:231
	v_lshl_add_u64 v[12:13], v[4:5], 1, v[80:81]
	v_lshlrev_b32_e32 v2, 12, v11
	s_waitcnt lgkmcnt(0)
	v_cvt_pk_bf16_f32 v21, v6, v7
	ds_read2_b32 v[6:7], v102 offset0:8 offset1:41
	v_lshl_add_u64 v[4:5], v[12:13], 0, v[2:3]
	global_store_dwordx4 v[4:5], v[18:21], off nt
	s_waitcnt lgkmcnt(0)
	v_cvt_pk_bf16_f32 v4, v6, v7
	ds_read2_b32 v[6:7], v102 offset0:74 offset1:107
	s_waitcnt lgkmcnt(0)
	v_cvt_pk_bf16_f32 v5, v6, v7
	ds_read2_b32 v[6:7], v102 offset0:140 offset1:173
	v_lshlrev_b32_e32 v2, 12, v10
	s_waitcnt lgkmcnt(0)
	v_cvt_pk_bf16_f32 v6, v6, v7
	ds_read2_b32 v[18:19], v102 offset0:206 offset1:239
	s_waitcnt lgkmcnt(0)
	v_cvt_pk_bf16_f32 v7, v18, v19
	v_lshl_add_u64 v[10:11], v[12:13], 0, v[2:3]
	ds_read2_b32 v[18:19], v102 offset0:16 offset1:49
	global_store_dwordx4 v[10:11], v[4:7], off nt
	v_lshlrev_b32_e32 v2, 12, v9
	s_waitcnt lgkmcnt(0)
	v_cvt_pk_bf16_f32 v4, v18, v19
	ds_read2_b32 v[6:7], v102 offset0:82 offset1:115
	s_waitcnt lgkmcnt(0)
	v_cvt_pk_bf16_f32 v5, v6, v7
	ds_read2_b32 v[6:7], v102 offset0:148 offset1:181
	s_waitcnt lgkmcnt(0)
	v_cvt_pk_bf16_f32 v6, v6, v7
	ds_read2_b32 v[10:11], v102 offset0:214 offset1:247
	s_waitcnt lgkmcnt(0)
	v_cvt_pk_bf16_f32 v7, v10, v11
	v_lshl_add_u64 v[18:19], v[12:13], 0, v[2:3]
	ds_read2_b32 v[10:11], v102 offset0:24 offset1:57
	global_store_dwordx4 v[18:19], v[4:7], off nt
	v_lshlrev_b32_e32 v2, 12, v8
	v_lshl_add_u64 v[8:9], v[12:13], 0, v[2:3]
	s_waitcnt lgkmcnt(0)
	v_cvt_pk_bf16_f32 v4, v10, v11
	ds_read2_b32 v[6:7], v102 offset0:90 offset1:123
	s_waitcnt lgkmcnt(0)
	v_cvt_pk_bf16_f32 v5, v6, v7
	ds_read2_b32 v[6:7], v102 offset0:156 offset1:189
	s_waitcnt lgkmcnt(0)
	v_cvt_pk_bf16_f32 v6, v6, v7
	ds_read2_b32 v[10:11], v102 offset0:222 offset1:255
	s_waitcnt lgkmcnt(0)
	v_cvt_pk_bf16_f32 v7, v10, v11
	global_store_dwordx4 v[8:9], v[4:7], off nt
	s_waitcnt lgkmcnt(0)

.LBB0_32:
	s_waitcnt vmcnt(30)
	ds_write2_b32 v100, v13, v17 offset1:66
	s_waitcnt vmcnt(28)
	ds_write2_b32 v100, v18, v20 offset0:132 offset1:198
	v_add_u32_e32 v13, 0x400, v100
	s_waitcnt vmcnt(26)
	ds_write2_b32 v13, v19, v21 offset0:8 offset1:74
	s_waitcnt vmcnt(24)
	ds_write2_b32 v13, v22, v23 offset0:140 offset1:206
	v_add_u32_e32 v13, 0x800, v100
	s_waitcnt vmcnt(22)
	ds_write2_b32 v13, v24, v25 offset0:16 offset1:82
	s_waitcnt vmcnt(20)
	ds_write2_b32 v13, v26, v28 offset0:148 offset1:214
	v_add_u32_e32 v13, 0xc00, v100
	s_waitcnt vmcnt(18)
	ds_write2_b32 v13, v27, v29 offset0:24 offset1:90
	s_waitcnt vmcnt(16)
	ds_write2_b32 v13, v30, v31 offset0:156 offset1:222
	v_add_u32_e32 v13, 0x1000, v100
	s_waitcnt vmcnt(14)
	ds_write2_b32 v13, v32, v33 offset0:32 offset1:98
	s_waitcnt vmcnt(12)
	ds_write2_b32 v13, v34, v36 offset0:164 offset1:230
	v_add_u32_e32 v13, 0x1400, v100
	s_waitcnt vmcnt(10)
	ds_write2_b32 v13, v35, v37 offset0:40 offset1:106
	s_waitcnt vmcnt(8)
	ds_write2_b32 v13, v38, v39 offset0:172 offset1:238
	v_add_u32_e32 v13, 0x1800, v100
	s_waitcnt vmcnt(6)
	ds_write2_b32 v13, v40, v41 offset0:48 offset1:114
	s_waitcnt vmcnt(4)
	ds_write2_b32 v13, v42, v44 offset0:180 offset1:246
	v_add_u32_e32 v13, 0x1c00, v100
	s_waitcnt vmcnt(2)
	ds_write2_b32 v13, v43, v45 offset0:56 offset1:122
	s_waitcnt vmcnt(0)
	ds_write2_b32 v13, v46, v47 offset0:188 offset1:254
	s_waitcnt lgkmcnt(0)
	ds_read2_b32 v[18:19], v102 offset1:33
	v_lshlrev_b32_e32 v2, 1, v2
	v_lshl_add_u64 v[24:25], v[84:85], 0, v[2:3]
	s_waitcnt lgkmcnt(0)
	v_mul_f32_e32 v13, v8, v18
	v_mul_f32_e32 v17, v9, v19
	v_cvt_pk_bf16_f32 v18, v13, v17
	ds_read2_b32 v[20:21], v102 offset0:66 offset1:99
	s_waitcnt lgkmcnt(0)
	v_mul_f32_e32 v13, v10, v20
	v_mul_f32_e32 v17, v11, v21
	v_cvt_pk_bf16_f32 v19, v13, v17
	ds_read2_b32 v[20:21], v102 offset0:132 offset1:165
	s_waitcnt lgkmcnt(0)
	v_mul_f32_e32 v13, v4, v20
	v_mul_f32_e32 v17, v5, v21
	v_cvt_pk_bf16_f32 v20, v13, v17
	ds_read2_b32 v[22:23], v102 offset0:198 offset1:231
	s_waitcnt lgkmcnt(0)
	v_mul_f32_e32 v2, v6, v22
	v_mul_f32_e32 v13, v7, v23
	v_cvt_pk_bf16_f32 v21, v2, v13
	ds_read2_b32 v[22:23], v102 offset0:8 offset1:41
	v_or_b32_e32 v2, v12, v101
	v_lshlrev_b32_e32 v2, 11, v2
	v_lshl_add_u64 v[26:27], v[24:25], 0, v[2:3]
	global_store_dwordx4 v[26:27], v[18:21], off nt
	s_waitcnt lgkmcnt(0)
	v_mul_f32_e32 v2, v8, v22
	v_mul_f32_e32 v13, v9, v23
	v_cvt_pk_bf16_f32 v18, v2, v13
	ds_read2_b32 v[20:21], v102 offset0:74 offset1:107
	s_waitcnt lgkmcnt(0)
	v_mul_f32_e32 v2, v10, v20
	v_mul_f32_e32 v13, v11, v21
	v_cvt_pk_bf16_f32 v19, v2, v13
	ds_read2_b32 v[20:21], v102 offset0:140 offset1:173
	s_waitcnt lgkmcnt(0)
	v_mul_f32_e32 v2, v4, v20
	v_mul_f32_e32 v13, v5, v21
	v_cvt_pk_bf16_f32 v20, v2, v13
	ds_read2_b32 v[22:23], v102 offset0:206 offset1:239
	s_waitcnt lgkmcnt(0)
	v_mul_f32_e32 v2, v6, v22
	v_mul_f32_e32 v13, v7, v23
	v_cvt_pk_bf16_f32 v21, v2, v13
	ds_read2_b32 v[22:23], v102 offset0:16 offset1:49
	v_or_b32_e32 v2, v12, v103
	v_lshlrev_b32_e32 v2, 11, v2
	v_lshl_add_u64 v[26:27], v[24:25], 0, v[2:3]
	global_store_dwordx4 v[26:27], v[18:21], off nt
	s_waitcnt lgkmcnt(0)
	v_mul_f32_e32 v2, v8, v22
	v_mul_f32_e32 v13, v9, v23
	v_cvt_pk_bf16_f32 v18, v2, v13
	ds_read2_b32 v[20:21], v102 offset0:82 offset1:115
	s_waitcnt lgkmcnt(0)
	v_mul_f32_e32 v2, v10, v20
	v_mul_f32_e32 v13, v11, v21
	v_cvt_pk_bf16_f32 v19, v2, v13
	ds_read2_b32 v[20:21], v102 offset0:148 offset1:181
	s_waitcnt lgkmcnt(0)
	v_mul_f32_e32 v2, v4, v20
	v_mul_f32_e32 v13, v5, v21
	v_cvt_pk_bf16_f32 v20, v2, v13
	ds_read2_b32 v[22:23], v102 offset0:214 offset1:247
	s_waitcnt lgkmcnt(0)
	v_mul_f32_e32 v2, v6, v22
	v_mul_f32_e32 v13, v7, v23
	v_cvt_pk_bf16_f32 v21, v2, v13
	ds_read2_b32 v[22:23], v102 offset0:24 offset1:57
	v_or_b32_e32 v2, v12, v104
	v_lshlrev_b32_e32 v2, 11, v2
	v_lshl_add_u64 v[26:27], v[24:25], 0, v[2:3]
	global_store_dwordx4 v[26:27], v[18:21], off nt
	s_waitcnt lgkmcnt(0)
	v_mul_f32_e32 v2, v8, v22
	v_mul_f32_e32 v8, v9, v23
	v_cvt_pk_bf16_f32 v8, v2, v8
	ds_read2_b32 v[18:19], v102 offset0:90 offset1:123
	s_waitcnt lgkmcnt(0)
	v_mul_f32_e32 v9, v11, v19
	v_mul_f32_e32 v2, v10, v18
	v_cvt_pk_bf16_f32 v9, v2, v9
	ds_read2_b32 v[10:11], v102 offset0:156 offset1:189
	s_waitcnt lgkmcnt(0)
	v_mul_f32_e32 v2, v4, v10
	v_mul_f32_e32 v4, v5, v11
	v_cvt_pk_bf16_f32 v10, v2, v4
	ds_read2_b32 v[4:5], v102 offset0:222 offset1:255
	s_waitcnt lgkmcnt(0)
	v_mul_f32_e32 v2, v6, v4
	v_mul_f32_e32 v4, v7, v5
	v_cvt_pk_bf16_f32 v11, v2, v4
	v_or_b32_e32 v2, v12, v105
	v_lshlrev_b32_e32 v2, 11, v2
	v_lshl_add_u64 v[4:5], v[24:25], 0, v[2:3]
	global_store_dwordx4 v[4:5], v[8:11], off nt
	s_waitcnt lgkmcnt(0)

.LBB0_34:
	s_andn2_saveexec_b64 s[60:61], s[60:61]
	s_cbranch_execz .LBB0_36
	v_add_u32_e32 v2, 0xffffd400, v16
	v_mul_u32_u24_e32 v2, 0xba2f, v2
	v_lshrrev_b32_e32 v7, 26, v2
	v_mul_u32_u24_e32 v2, 0xfa80, v7
	v_add_u32_e32 v2, v2, v16
	v_add_u16_e32 v2, 0xd400, v2
	v_ashrrev_i16_e32 v4, 15, v2
	v_lshrrev_b16_e32 v4, 11, v4
	v_add_u16_e32 v4, v2, v4
	v_ashrrev_i16_e32 v6, 5, v4
	v_lshlrev_b32_sdwa v6, v110, sext(v6) dst_sel:DWORD dst_unused:UNUSED_PAD src0_sel:DWORD src1_sel:WORD_0
	v_and_b32_e32 v4, 0xffffffe0, v4
	v_or_b32_e32 v10, v6, v73
	v_sub_u16_e32 v2, v2, v4
	v_mov_b64_e32 v[4:5], s[20:21]
	v_ashrrev_i32_e32 v11, 31, v10
	v_mad_u64_u32 v[8:9], s[62:63], v7, s90, v[4:5]
	v_lshlrev_b32_sdwa v4, v109, sext(v2) dst_sel:DWORD dst_unused:UNUSED_PAD src0_sel:DWORD src1_sel:WORD_0
	v_lshlrev_b64 v[10:11], 12, v[10:11]
	v_lshl_add_u64 v[8:9], v[8:9], 0, v[10:11]
	v_ashrrev_i32_e32 v5, 31, v4
	v_lshl_add_u64 v[8:9], v[4:5], 2, v[8:9]
	v_lshlrev_b32_e32 v2, 2, v70
	v_lshl_add_u64 v[8:9], v[8:9], 0, v[2:3]
	v_add_co_u32_e32 v10, vcc, s76, v8
	s_movk_i32 s3, 0x4000
	s_nop 0
	v_addc_co_u32_e32 v11, vcc, 0, v9, vcc
	v_add_co_u32_e32 v12, vcc, s3, v8
	s_movk_i32 s3, 0x6000
	s_nop 0
	v_addc_co_u32_e32 v13, vcc, 0, v9, vcc
	v_add_co_u32_e32 v18, vcc, s3, v8
	s_mov_b32 s3, 0xa000
	s_nop 0
	v_addc_co_u32_e32 v19, vcc, 0, v9, vcc
	v_add_co_u32_e32 v20, vcc, s80, v8
	s_nop 1
	v_addc_co_u32_e32 v21, vcc, 0, v9, vcc
	v_add_co_u32_e32 v22, vcc, s3, v8
	s_mov_b32 s3, 0xc000
	s_nop 0
	v_addc_co_u32_e32 v23, vcc, 0, v9, vcc
	v_add_co_u32_e32 v24, vcc, s3, v8
	s_mov_b32 s3, 0xe000
	s_nop 0
	v_addc_co_u32_e32 v25, vcc, 0, v9, vcc
	v_add_co_u32_e32 v26, vcc, s3, v8
	s_mov_b32 s3, 0x12000
	s_nop 0
	v_addc_co_u32_e32 v27, vcc, 0, v9, vcc
	global_load_dword v2, v[8:9], off nt
	global_load_dword v5, v[10:11], off nt
	global_load_dword v17, v[12:13], off nt
	global_load_dword v30, v[18:19], off nt
	global_load_dword v31, v[20:21], off nt
	global_load_dword v32, v[22:23], off nt
	global_load_dword v33, v[24:25], off nt
	global_load_dword v34, v[26:27], off nt
	v_add_co_u32_e32 v10, vcc, s81, v8
	s_nop 1
	v_addc_co_u32_e32 v11, vcc, 0, v9, vcc
	v_add_co_u32_e32 v12, vcc, s3, v8
	s_mov_b32 s3, 0x14000
	s_nop 0
	v_addc_co_u32_e32 v13, vcc, 0, v9, vcc
	v_add_co_u32_e32 v18, vcc, s3, v8
	s_mov_b32 s3, 0x1a000
	s_nop 0
	v_addc_co_u32_e32 v19, vcc, 0, v9, vcc
	v_add_co_u32_e32 v20, vcc, s82, v8
	s_nop 1
	v_addc_co_u32_e32 v21, vcc, 0, v9, vcc
	v_add_co_u32_e32 v22, vcc, s83, v8
	s_nop 1
	v_addc_co_u32_e32 v23, vcc, 0, v9, vcc
	v_add_co_u32_e32 v24, vcc, s3, v8
	s_mov_b32 s3, 0x1c000
	s_nop 0
	v_addc_co_u32_e32 v25, vcc, 0, v9, vcc
	v_add_co_u32_e32 v26, vcc, s3, v8
	s_mov_b32 s3, 0x1e000
	s_nop 0
	v_addc_co_u32_e32 v27, vcc, 0, v9, vcc
	v_add_co_u32_e32 v28, vcc, s3, v8
	s_mov_b32 s3, 0x22000
	s_nop 0
	v_addc_co_u32_e32 v29, vcc, 0, v9, vcc
	global_load_dword v35, v[10:11], off nt
	global_load_dword v36, v[12:13], off nt
	global_load_dword v37, v[18:19], off nt
	global_load_dword v38, v[20:21], off nt
	global_load_dword v39, v[22:23], off nt
	global_load_dword v40, v[24:25], off nt
	global_load_dword v41, v[26:27], off nt
	global_load_dword v42, v[28:29], off nt
	v_add_co_u32_e32 v10, vcc, s75, v8
	s_nop 1
	v_addc_co_u32_e32 v11, vcc, 0, v9, vcc
	v_add_co_u32_e32 v12, vcc, s3, v8
	s_mov_b32 s3, 0x24000
	s_nop 0
	v_addc_co_u32_e32 v13, vcc, 0, v9, vcc
	v_add_co_u32_e32 v18, vcc, s3, v8
	s_mov_b32 s3, 0x26000
	s_nop 0
	v_addc_co_u32_e32 v19, vcc, 0, v9, vcc
	v_add_co_u32_e32 v20, vcc, s3, v8
	s_mov_b32 s3, 0x2a000
	s_nop 0
	v_addc_co_u32_e32 v21, vcc, 0, v9, vcc
	v_add_co_u32_e32 v22, vcc, s84, v8
	s_nop 1
	v_addc_co_u32_e32 v23, vcc, 0, v9, vcc
	v_add_co_u32_e32 v24, vcc, s3, v8
	s_mov_b32 s3, 0x2e000
	s_nop 0
	v_addc_co_u32_e32 v25, vcc, 0, v9, vcc
	v_add_co_u32_e32 v26, vcc, s85, v8
	s_nop 1
	v_addc_co_u32_e32 v27, vcc, 0, v9, vcc
	v_add_co_u32_e32 v28, vcc, s3, v8
	s_mov_b32 s3, 0x32000
	s_nop 0
	v_addc_co_u32_e32 v29, vcc, 0, v9, vcc
	global_load_dword v43, v[10:11], off nt
	global_load_dword v44, v[12:13], off nt
	global_load_dword v45, v[18:19], off nt
	global_load_dword v46, v[20:21], off nt
	global_load_dword v47, v[22:23], off nt
	global_load_dword v48, v[24:25], off nt
	global_load_dword v49, v[26:27], off nt
	s_nop 0
	global_load_dword v28, v[28:29], off nt
	v_add_co_u32_e32 v10, vcc, s86, v8
	s_nop 1
	v_addc_co_u32_e32 v11, vcc, 0, v9, vcc
	v_add_co_u32_e32 v12, vcc, s3, v8
	s_mov_b32 s3, 0x34000
	s_nop 0
	v_addc_co_u32_e32 v13, vcc, 0, v9, vcc
	v_add_co_u32_e32 v18, vcc, s3, v8
	s_mov_b32 s3, 0x36000
	s_nop 0
	v_addc_co_u32_e32 v19, vcc, 0, v9, vcc
	v_add_co_u32_e32 v20, vcc, s3, v8
	s_mov_b32 s3, 0x3a000
	s_nop 0
	v_addc_co_u32_e32 v21, vcc, 0, v9, vcc
	v_add_co_u32_e32 v22, vcc, s87, v8
	s_nop 1
	v_addc_co_u32_e32 v23, vcc, 0, v9, vcc
	v_add_co_u32_e32 v24, vcc, s3, v8
	s_mov_b32 s3, 0x3c000
	s_nop 0
	v_addc_co_u32_e32 v25, vcc, 0, v9, vcc
	v_add_co_u32_e32 v26, vcc, s3, v8
	s_mov_b32 s3, 0x580000
	s_nop 0
	v_addc_co_u32_e32 v27, vcc, 0, v9, vcc
	v_add_co_u32_e32 v8, vcc, s79, v8
	s_nop 1
	v_addc_co_u32_e32 v9, vcc, 0, v9, vcc
	global_load_dword v10, v[10:11], off nt
	s_nop 0
	global_load_dword v11, v[12:13], off nt
	s_nop 0
	global_load_dword v12, v[18:19], off nt
	global_load_dword v13, v[20:21], off nt
	s_nop 0
	global_load_dword v18, v[22:23], off nt
	global_load_dword v19, v[24:25], off nt
	global_load_dword v20, v[26:27], off nt
	s_nop 0
	global_load_dword v8, v[8:9], off nt
	s_waitcnt vmcnt(30)
	ds_write2_b32 v100, v2, v5 offset1:66
	s_waitcnt vmcnt(28)
	ds_write2_b32 v100, v17, v30 offset0:132 offset1:198
	v_add_u32_e32 v2, 0x400, v100
	s_waitcnt vmcnt(26)
	ds_write2_b32 v2, v31, v32 offset0:8 offset1:74
	s_waitcnt vmcnt(24)
	ds_write2_b32 v2, v33, v34 offset0:140 offset1:206
	v_add_u32_e32 v2, 0x800, v100
	s_waitcnt vmcnt(22)
	ds_write2_b32 v2, v35, v36 offset0:16 offset1:82
	s_waitcnt vmcnt(20)
	ds_write2_b32 v2, v37, v38 offset0:148 offset1:214
	v_add_u32_e32 v2, 0xc00, v100
	s_waitcnt vmcnt(18)
	ds_write2_b32 v2, v39, v40 offset0:24 offset1:90
	s_waitcnt vmcnt(16)
	ds_write2_b32 v2, v41, v42 offset0:156 offset1:222
	v_add_u32_e32 v2, 0x1000, v100
	s_waitcnt vmcnt(14)
	ds_write2_b32 v2, v43, v44 offset0:32 offset1:98
	s_waitcnt vmcnt(12)
	ds_write2_b32 v2, v45, v46 offset0:164 offset1:230
	v_add_u32_e32 v2, 0x1400, v100
	s_waitcnt vmcnt(10)
	ds_write2_b32 v2, v47, v48 offset0:40 offset1:106
	s_waitcnt vmcnt(8)
	ds_write2_b32 v2, v49, v28 offset0:172 offset1:238
	v_add_u32_e32 v2, 0x1800, v100
	s_waitcnt vmcnt(6)
	ds_write2_b32 v2, v10, v11 offset0:48 offset1:114
	s_waitcnt vmcnt(4)
	ds_write2_b32 v2, v12, v13 offset0:180 offset1:246
	v_add_u32_e32 v2, 0x1c00, v100
	s_waitcnt vmcnt(2)
	ds_write2_b32 v2, v18, v19 offset0:56 offset1:122
	s_waitcnt vmcnt(0)
	ds_write2_b32 v2, v20, v8 offset0:188 offset1:254
	s_waitcnt lgkmcnt(0)
	ds_read2_b32 v[8:9], v102 offset1:33
	v_mov_b64_e32 v[12:13], s[50:51]
	s_waitcnt lgkmcnt(0)
	v_cvt_pk_bf16_f32 v8, v8, v9
	ds_read2_b32 v[10:11], v102 offset0:66 offset1:99
	v_mad_u64_u32 v[12:13], s[62:63], v7, s3, v[12:13]
	v_ashrrev_i32_e32 v7, 31, v6
	s_waitcnt lgkmcnt(0)
	v_cvt_pk_bf16_f32 v9, v10, v11
	ds_read2_b32 v[10:11], v102 offset0:132 offset1:165
	v_lshl_add_u64 v[6:7], v[6:7], 1, v[12:13]
	v_lshlrev_b32_e32 v2, 1, v72
	s_waitcnt lgkmcnt(0)
	v_cvt_pk_bf16_f32 v10, v10, v11
	ds_read2_b32 v[18:19], v102 offset0:198 offset1:231
	v_lshl_add_u64 v[12:13], v[6:7], 0, v[2:3]
	v_or_b32_e32 v2, v4, v101
	s_waitcnt lgkmcnt(0)
	v_cvt_pk_bf16_f32 v11, v18, v19
	v_mul_i32_i24_e32 v18, 0xb00, v2
	v_ashrrev_i32_e32 v19, 31, v18
	ds_read2_b32 v[6:7], v102 offset0:8 offset1:41
	v_lshl_add_u64 v[18:19], v[18:19], 1, v[12:13]
	v_or_b32_e32 v2, v4, v103
	global_store_dwordx4 v[18:19], v[8:11], off nt
	s_waitcnt lgkmcnt(0)
	v_cvt_pk_bf16_f32 v6, v6, v7
	ds_read2_b32 v[8:9], v102 offset0:74 offset1:107
	v_mul_i32_i24_e32 v18, 0xb00, v2
	s_waitcnt lgkmcnt(0)
	v_cvt_pk_bf16_f32 v7, v8, v9
	ds_read2_b32 v[8:9], v102 offset0:140 offset1:173
	v_ashrrev_i32_e32 v19, 31, v18
	s_waitcnt lgkmcnt(0)
	v_cvt_pk_bf16_f32 v8, v8, v9
	ds_read2_b32 v[10:11], v102 offset0:206 offset1:239
	s_waitcnt lgkmcnt(0)
	v_cvt_pk_bf16_f32 v9, v10, v11
	v_lshl_add_u64 v[18:19], v[18:19], 1, v[12:13]
	v_or_b32_e32 v2, v4, v104
	ds_read2_b32 v[10:11], v102 offset0:16 offset1:49
	global_store_dwordx4 v[18:19], v[6:9], off nt
	v_mul_i32_i24_e32 v18, 0xb00, v2
	v_ashrrev_i32_e32 v19, 31, v18
	s_waitcnt lgkmcnt(0)
	v_cvt_pk_bf16_f32 v6, v10, v11
	ds_read2_b32 v[8:9], v102 offset0:82 offset1:115
	s_waitcnt lgkmcnt(0)
	v_cvt_pk_bf16_f32 v7, v8, v9
	ds_read2_b32 v[8:9], v102 offset0:148 offset1:181
	v_or_b32_e32 v2, v4, v105
	s_waitcnt lgkmcnt(0)
	v_cvt_pk_bf16_f32 v8, v8, v9
	ds_read2_b32 v[10:11], v102 offset0:214 offset1:247
	s_waitcnt lgkmcnt(0)
	v_cvt_pk_bf16_f32 v9, v10, v11
	v_lshl_add_u64 v[18:19], v[18:19], 1, v[12:13]
	v_mul_i32_i24_e32 v4, 0xb00, v2
	ds_read2_b32 v[10:11], v102 offset0:24 offset1:57
	global_store_dwordx4 v[18:19], v[6:9], off nt
	v_ashrrev_i32_e32 v5, 31, v4
	v_lshl_add_u64 v[4:5], v[4:5], 1, v[12:13]
	s_waitcnt lgkmcnt(0)
	v_cvt_pk_bf16_f32 v6, v10, v11
	ds_read2_b32 v[8:9], v102 offset0:90 offset1:123
	s_waitcnt lgkmcnt(0)
	v_cvt_pk_bf16_f32 v7, v8, v9
	ds_read2_b32 v[8:9], v102 offset0:156 offset1:189
	s_waitcnt lgkmcnt(0)
	v_cvt_pk_bf16_f32 v8, v8, v9
	ds_read2_b32 v[10:11], v102 offset0:222 offset1:255
	s_waitcnt lgkmcnt(0)
	v_cvt_pk_bf16_f32 v9, v10, v11
	global_store_dwordx4 v[4:5], v[6:9], off nt
	s_waitcnt lgkmcnt(0)

.LBB0_45:
	global_load_dwordx4 v[10:13], v[92:93], off offset:-3072 nt
	global_load_dwordx4 v[6:9], v[92:93], off offset:-2048 nt
	global_load_dwordx4 v[22:25], v[92:93], off offset:-4096 nt
	v_add_co_u32_e32 v4, vcc, 0xffffd000, v92
	s_mov_b32 s3, 0x6000000
	s_nop 0
	v_addc_co_u32_e32 v5, vcc, -1, v93, vcc
	global_load_dwordx4 v[66:69], v[4:5], off offset:-3072 nt
	global_load_dwordx4 v[62:65], v[4:5], off offset:-2048 nt
	global_load_dwordx4 v[58:61], v[4:5], off offset:-1024 nt
	global_load_dwordx4 v[54:57], v[4:5], off nt
	v_add_co_u32_e32 v4, vcc, 0xffffe000, v92
	s_waitcnt vmcnt(6)
	v_mul_f32_e32 v2, v11, v11
	v_addc_co_u32_e32 v5, vcc, -1, v93, vcc
	global_load_dwordx4 v[50:53], v[4:5], off offset:-3072 nt
	global_load_dwordx4 v[46:49], v[4:5], off offset:-2048 nt
	global_load_dwordx4 v[42:45], v[4:5], off offset:-1024 nt
	global_load_dwordx4 v[38:41], v[4:5], off nt
	v_add_co_u32_e32 v4, vcc, 0xfffff000, v92
	s_waitcnt vmcnt(8)
	v_mul_f32_e32 v98, v23, v23
	v_addc_co_u32_e32 v5, vcc, -1, v93, vcc
	global_load_dwordx4 v[34:37], v[4:5], off offset:-3072 nt
	global_load_dwordx4 v[30:33], v[4:5], off offset:-2048 nt
	global_load_dwordx4 v[26:29], v[4:5], off offset:-1024 nt
	global_load_dwordx4 v[18:21], v[92:93], off offset:-1024 nt
	global_load_dwordx4 v[14:17], v[92:93], off nt
	v_mul_f32_e32 v4, v13, v13
	v_mul_f32_e32 v99, v25, v25
	v_fmac_f32_e32 v2, v10, v10
	v_fmac_f32_e32 v4, v12, v12
	v_fmac_f32_e32 v98, v22, v22
	v_fmac_f32_e32 v99, v24, v24
	v_add_f32_e32 v118, v2, v4
	v_add_f32_e32 v2, v98, v99
	s_waitcnt vmcnt(12)
	v_mul_f32_e32 v4, v67, v67
	v_mul_f32_e32 v98, v69, v69
	s_waitcnt vmcnt(11)
	v_mul_f32_e32 v99, v63, v63
	s_waitcnt lgkmcnt(0)
	v_mul_f32_e32 v119, v65, v65
	s_waitcnt vmcnt(10)
	v_mul_f32_e32 v120, v59, v59
	v_mul_f32_e32 v121, v61, v61
	v_fmac_f32_e32 v4, v66, v66
	v_fmac_f32_e32 v98, v68, v68
	v_fmac_f32_e32 v99, v62, v62
	v_fmac_f32_e32 v119, v64, v64
	s_waitcnt vmcnt(9)
	v_mul_f32_e32 v122, v55, v55
	v_mul_f32_e32 v123, v57, v57
	v_fmac_f32_e32 v120, v58, v58
	v_fmac_f32_e32 v121, v60, v60
	v_add_f32_e32 v4, v4, v98
	v_add_f32_e32 v98, v99, v119
	v_fmac_f32_e32 v122, v54, v54
	v_fmac_f32_e32 v123, v56, v56
	v_add_f32_e32 v99, v120, v121
	v_add_f32_e32 v4, v4, v98
	v_add_f32_e32 v119, v122, v123
	v_add_f32_e32 v4, v4, v99
	v_add_f32_e32 v4, v4, v119
	ds_bpermute_b32 v99, v111, v4
	v_mul_f32_e32 v5, v7, v7
	v_fmac_f32_e32 v5, v6, v6
	v_cvt_pk_bf16_f32 v66, v66, v67
	v_cvt_pk_bf16_f32 v67, v68, v69
	s_waitcnt lgkmcnt(0)
	v_add_f32_e32 v4, v4, v99
	ds_bpermute_b32 v99, v112, v4
	s_waitcnt lgkmcnt(0)
	v_add_f32_e32 v4, v4, v99
	ds_bpermute_b32 v99, v113, v4
	s_waitcnt lgkmcnt(0)
	v_add_f32_e32 v4, v4, v99
	ds_bpermute_b32 v99, v114, v4
	s_waitcnt lgkmcnt(0)
	v_add_f32_e32 v4, v4, v99
	ds_bpermute_b32 v99, v115, v4
	s_waitcnt vmcnt(8)
	v_mul_f32_e32 v124, v51, v51
	v_mul_f32_e32 v125, v53, v53
	s_waitcnt vmcnt(7)
	v_mul_f32_e32 v126, v47, v47
	v_mul_f32_e32 v127, v49, v49
	v_fmac_f32_e32 v124, v50, v50
	v_fmac_f32_e32 v125, v52, v52
	v_fmac_f32_e32 v126, v46, v46
	v_fmac_f32_e32 v127, v48, v48
	s_waitcnt vmcnt(4)
	v_mul_f32_e32 v120, v35, v35
	v_mul_f32_e32 v121, v37, v37
	s_waitcnt vmcnt(3)
	v_mul_f32_e32 v122, v31, v31
	v_mul_f32_e32 v123, v33, v33
	s_waitcnt vmcnt(2)
	v_mul_f32_e32 v132, v27, v27
	v_mul_f32_e32 v133, v29, v29
	v_add_f32_e32 v98, v124, v125
	v_add_f32_e32 v119, v126, v127
	v_fmac_f32_e32 v120, v34, v34
	v_fmac_f32_e32 v121, v36, v36
	v_fmac_f32_e32 v122, v30, v30
	v_fmac_f32_e32 v123, v32, v32
	v_fmac_f32_e32 v132, v26, v26
	v_fmac_f32_e32 v133, v28, v28
	v_add_f32_e32 v98, v98, v119
	v_add_f32_e32 v119, v120, v121
	v_add_f32_e32 v120, v122, v123
	v_add_f32_e32 v121, v132, v133
	v_add_f32_e32 v119, v119, v120
	v_add_f32_e32 v119, v119, v121
	v_add_f32_e32 v119, v119, v2
	s_waitcnt lgkmcnt(0)
	v_add_f32_e32 v2, v4, v99
	v_mul_f32_e32 v99, v9, v9
	v_fmac_f32_e32 v99, v8, v8
	v_add_f32_e32 v5, v5, v99
	v_add_f32_e32 v5, v118, v5
	s_waitcnt vmcnt(1)
	v_mul_f32_e32 v99, v19, v19
	v_mul_f32_e32 v118, v21, v21
	v_fmac_f32_e32 v99, v18, v18
	v_fmac_f32_e32 v118, v20, v20
	v_mul_f32_e32 v128, v43, v43
	v_mul_f32_e32 v129, v45, v45
	v_add_f32_e32 v99, v99, v118
	v_mul_f32_e32 v130, v39, v39
	v_mul_f32_e32 v131, v41, v41
	v_fmac_f32_e32 v128, v42, v42
	v_fmac_f32_e32 v129, v44, v44
	v_add_f32_e32 v5, v5, v99
	s_waitcnt vmcnt(0)
	v_mul_f32_e32 v99, v15, v15
	v_mul_f32_e32 v118, v17, v17
	v_fmac_f32_e32 v130, v38, v38
	v_fmac_f32_e32 v131, v40, v40
	v_add_f32_e32 v124, v128, v129
	v_fmac_f32_e32 v99, v14, v14
	v_fmac_f32_e32 v118, v16, v16
	v_add_f32_e32 v125, v130, v131
	v_add_f32_e32 v98, v98, v124
	v_add_f32_e32 v99, v99, v118
	v_add_f32_e32 v98, v98, v125
	v_add_f32_e32 v5, v5, v99
	ds_bpermute_b32 v120, v111, v98
	ds_bpermute_b32 v121, v111, v119
	ds_bpermute_b32 v99, v111, v5
	ds_bpermute_b32 v4, v116, v2
	s_waitcnt lgkmcnt(3)
	v_add_f32_e32 v98, v98, v120
	s_waitcnt lgkmcnt(2)
	v_add_f32_e32 v119, v119, v121
	s_waitcnt lgkmcnt(1)
	v_add_f32_e32 v5, v5, v99
	ds_bpermute_b32 v118, v112, v98
	ds_bpermute_b32 v120, v112, v119
	ds_bpermute_b32 v99, v112, v5
	s_waitcnt lgkmcnt(2)
	v_add_f32_e32 v98, v98, v118
	s_waitcnt lgkmcnt(1)
	v_add_f32_e32 v119, v119, v120
	s_waitcnt lgkmcnt(0)
	v_add_f32_e32 v5, v5, v99
	ds_bpermute_b32 v118, v113, v98
	ds_bpermute_b32 v120, v113, v119
	ds_bpermute_b32 v99, v113, v5
	s_waitcnt lgkmcnt(2)
	v_add_f32_e32 v98, v98, v118
	s_waitcnt lgkmcnt(1)
	v_add_f32_e32 v119, v119, v120
	s_waitcnt lgkmcnt(0)
	v_add_f32_e32 v5, v5, v99
	ds_bpermute_b32 v118, v114, v98
	ds_bpermute_b32 v120, v114, v119
	ds_bpermute_b32 v99, v114, v5
	s_waitcnt lgkmcnt(2)
	v_add_f32_e32 v98, v98, v118
	s_waitcnt lgkmcnt(1)
	v_add_f32_e32 v119, v119, v120
	s_waitcnt lgkmcnt(0)
	v_add_f32_e32 v5, v5, v99
	ds_bpermute_b32 v118, v115, v98
	ds_bpermute_b32 v120, v115, v119
	ds_bpermute_b32 v99, v115, v5
	s_waitcnt lgkmcnt(2)
	v_add_f32_e32 v122, v98, v118
	s_waitcnt lgkmcnt(1)
	v_add_f32_e32 v120, v119, v120
	s_waitcnt lgkmcnt(0)
	v_add_f32_e32 v118, v5, v99
	ds_bpermute_b32 v123, v116, v122
	ds_bpermute_b32 v121, v116, v120
	ds_bpermute_b32 v119, v116, v118
	v_lshl_add_u64 v[98:99], s[46:47], 0, v[94:95]
	v_add_co_u32_e32 v68, vcc, s3, v98
	s_nop 1
	v_addc_co_u32_e32 v69, vcc, 0, v99, vcc
	global_store_dwordx2 v[68:69], v[66:67], off nt
	v_cvt_pk_bf16_f32 v62, v62, v63
	v_cvt_pk_bf16_f32 v63, v64, v65
	global_store_dwordx2 v[68:69], v[62:63], off offset:512 nt
	v_cvt_pk_bf16_f32 v58, v58, v59
	v_cvt_pk_bf16_f32 v59, v60, v61
	global_store_dwordx2 v[68:69], v[58:59], off offset:1024 nt
	v_cvt_pk_bf16_f32 v54, v54, v55
	v_cvt_pk_bf16_f32 v55, v56, v57
	global_store_dwordx2 v[68:69], v[54:55], off offset:1536 nt
	v_lshl_add_u64 v[54:55], s[46:47], 0, v[96:97]
	s_and_saveexec_b64 s[30:31], s[8:9]
	s_cbranch_execz .LBB0_47
	v_add_co_u32_e32 v56, vcc, 0x100000, v54
	v_add_f32_e32 v2, v2, v4
	s_nop 0
	v_addc_co_u32_e32 v57, vcc, 0, v55, vcc
	v_mov_b32_e32 v4, v3
	v_mov_b32_e32 v5, v3
	global_store_dwordx4 v[56:57], v[2:5], off nt
.LBB0_47:
	s_or_b64 exec, exec, s[30:31]
	s_nop 0
	v_cvt_pk_bf16_f32 v4, v50, v51
	v_add_co_u32_e32 v50, vcc, 0x6000000, v98
	v_cvt_pk_bf16_f32 v5, v52, v53
	s_nop 1
	v_addc_co_u32_e32 v51, vcc, 0, v99, vcc
	global_store_dwordx2 v[50:51], v[4:5], off offset:2048 nt
	v_cvt_pk_bf16_f32 v4, v46, v47
	v_cvt_pk_bf16_f32 v5, v48, v49
	global_store_dwordx2 v[50:51], v[4:5], off offset:2560 nt
	v_cvt_pk_bf16_f32 v4, v42, v43
	v_cvt_pk_bf16_f32 v5, v44, v45
	global_store_dwordx2 v[50:51], v[4:5], off offset:3072 nt
	v_cvt_pk_bf16_f32 v4, v38, v39
	v_cvt_pk_bf16_f32 v5, v40, v41
	global_store_dwordx2 v[50:51], v[4:5], off offset:3584 nt
	s_and_saveexec_b64 s[30:31], s[8:9]
	s_cbranch_execz .LBB0_49
	v_add_co_u32_e32 v38, vcc, 0x100000, v54
	s_waitcnt lgkmcnt(2)
	v_add_f32_e32 v2, v122, v123
	v_addc_co_u32_e32 v39, vcc, 0, v55, vcc
	v_mov_b32_e32 v4, v3
	v_mov_b32_e32 v5, v3
	global_store_dwordx4 v[38:39], v[2:5], off offset:16 nt
.LBB0_49:
	s_or_b64 exec, exec, s[30:31]
	s_nop 0
	v_cvt_pk_bf16_f32 v4, v34, v35
	v_add_co_u32_e32 v34, vcc, 0x6001000, v98
	v_cvt_pk_bf16_f32 v5, v36, v37
	s_nop 1
	v_addc_co_u32_e32 v35, vcc, 0, v99, vcc
	global_store_dwordx2 v[34:35], v[4:5], off nt
	v_cvt_pk_bf16_f32 v4, v30, v31
	v_cvt_pk_bf16_f32 v5, v32, v33
	global_store_dwordx2 v[34:35], v[4:5], off offset:512 nt
	v_cvt_pk_bf16_f32 v4, v26, v27
	v_cvt_pk_bf16_f32 v5, v28, v29
	global_store_dwordx2 v[34:35], v[4:5], off offset:1024 nt
	v_cvt_pk_bf16_f32 v4, v22, v23
	v_cvt_pk_bf16_f32 v5, v24, v25
	global_store_dwordx2 v[34:35], v[4:5], off offset:1536 nt
	s_and_saveexec_b64 s[30:31], s[8:9]
	s_cbranch_execz .LBB0_51
	v_add_co_u32_e32 v22, vcc, 0x100000, v54
	s_waitcnt lgkmcnt(1)
	v_add_f32_e32 v2, v120, v121
	v_addc_co_u32_e32 v23, vcc, 0, v55, vcc
	v_mov_b32_e32 v4, v3
	v_mov_b32_e32 v5, v3
	global_store_dwordx4 v[22:23], v[2:5], off offset:32 nt
.LBB0_51:
	s_or_b64 exec, exec, s[30:31]
	s_nop 0
	v_cvt_pk_bf16_f32 v4, v10, v11
	v_add_co_u32_e32 v10, vcc, 0x6001000, v98
	v_cvt_pk_bf16_f32 v5, v12, v13
	s_nop 1
	v_addc_co_u32_e32 v11, vcc, 0, v99, vcc
	global_store_dwordx2 v[10:11], v[4:5], off offset:2048 nt
	v_cvt_pk_bf16_f32 v4, v6, v7
	v_cvt_pk_bf16_f32 v5, v8, v9
	global_store_dwordx2 v[10:11], v[4:5], off offset:2560 nt
	v_cvt_pk_bf16_f32 v4, v18, v19
	v_cvt_pk_bf16_f32 v5, v20, v21
	global_store_dwordx2 v[10:11], v[4:5], off offset:3072 nt
	v_cvt_pk_bf16_f32 v4, v14, v15
	v_cvt_pk_bf16_f32 v5, v16, v17
	global_store_dwordx2 v[10:11], v[4:5], off offset:3584 nt
	s_and_saveexec_b64 s[30:31], s[8:9]
	s_cbranch_execz .LBB0_44
	v_add_co_u32_e32 v6, vcc, 0x100000, v54
	s_waitcnt lgkmcnt(0)
	v_add_f32_e32 v2, v118, v119
	v_addc_co_u32_e32 v7, vcc, 0, v55, vcc
	v_mov_b32_e32 v4, v3
	v_mov_b32_e32 v5, v3
	global_store_dwordx4 v[6:7], v[2:5], off offset:48 nt
	s_branch .LBB0_44
